# pre-P1 seam keeps 768 layer-1 w_in items, the P1 idle slot of workgroups 192..255 converts 1792 (split chosen with an amplified phase timer)
# speedup vs baseline: 1.0070x; 1.0070x over previous
; __global__ void __launch_bounds__(512, 2) mk_fwd(Args args) {
;     ...
;     if (IN(0) && IN(1)) { if (DEPTH == 2) { xcd_barrier_arrive(xbar); CONVERT_ITEMS(I_L, I_L + 1280); xcd_barrier_wait(xbar); } else xcd_barrier(xbar); }
.LBB0_160:
	s_or_b64 exec, exec, s[0:1]
	v_mov_b32_e32 v0, v252
	s_lshl_b32 s14, s96, 3
	v_readfirstlane_b32 s0, v0
	s_ashr_i32 s2, s0, 6
	s_add_i32 s3, s14, s2
	s_lshl_b32 s0, s86, 3
	s_add_i32 s15, s3, 0x1780
	v_writelane_b32 v253, s0, 34
	s_mov_b64 s[0:1], s[20:21]
	s_movk_i32 s100, 0x1c7f
	s_cmpk_eq_i32 s86, 0x100
	s_cselect_b32 s100, 0x1a7f, s100
	s_cmp_gt_i32 s15, s100
	s_cbranch_scc1 .LBB0_209
	s_add_u32 s24, s0, 0x200000
	s_addc_u32 s25, s1, 0
	s_add_u32 s26, s0, 0x3e00000
	s_addc_u32 s27, s1, 0
	s_add_u32 s28, s0, 0x4e00000
	s_addc_u32 s29, s1, 0
	s_add_u32 s30, s0, 0x5e00000
	s_addc_u32 s31, s1, 0
	s_add_u32 s34, s0, 0x10000
	s_addc_u32 s35, s1, 0
	v_and_b32_e32 v2, 63, v0
	v_bfe_u32 v80, v0, 4, 2
	v_bfe_u32 v82, v0, 3, 3
	v_lshlrev_b32_e32 v0, 3, v0
	s_add_u32 s37, s0, 0x14000
	s_mulk_i32 s2, 0x4100
	v_lshlrev_b32_e32 v68, 2, v2
	v_and_b32_e32 v0, 56, v0
	s_addc_u32 s38, s1, 0
	s_add_i32 s2, s2, 0
	v_and_b32_e32 v4, 60, v68
	v_mul_u32_u24_e32 v3, 0x104, v0
	v_lshlrev_b32_e32 v5, 2, v82
	v_readlane_b32 s40, v253, 18
	v_lshl_add_u32 v1, v4, 2, s2
	s_movk_i32 s0, 0x104
	v_add3_u32 v83, s2, v3, v5
	v_readlane_b32 s50, v253, 28
	v_readlane_b32 s51, v253, 29
	v_or_b32_e32 v3, 4, v80
	v_mov_b32_e32 v69, 0
	v_mad_u32_u24 v81, v80, s0, v1
	v_readlane_b32 s41, v253, 19
	v_readlane_b32 s42, v253, 20
	v_readlane_b32 s43, v253, 21
	v_readlane_b32 s44, v253, 22
	v_readlane_b32 s45, v253, 23
	v_readlane_b32 s46, v253, 24
	v_readlane_b32 s47, v253, 25
	v_readlane_b32 s48, v253, 26
	v_readlane_b32 s49, v253, 27
	v_readlane_b32 s52, v253, 30
	v_readlane_b32 s53, v253, 31
	v_readlane_b32 s54, v253, 32
	v_readlane_b32 s55, v253, 33
	s_cmp_lg_u64 s[50:51], 0
	v_mul_u32_u24_e32 v3, 0x104, v3
	v_or_b32_e32 v84, 8, v82
	v_or_b32_e32 v85, 16, v82
	v_or_b32_e32 v86, 24, v82
	v_or_b32_e32 v87, 32, v82
	v_or_b32_e32 v88, 40, v82
	v_or_b32_e32 v89, 48, v82
	v_or_b32_e32 v90, 56, v82
	s_cselect_b64 s[0:1], -1, 0
	v_add_u32_e32 v91, s2, v68
	v_lshl_add_u64 v[70:71], s[16:17], 0, v[68:69]
	s_mov_b32 s39, 0x8000
	s_mov_b32 s40, 0x10000
	s_mov_b32 s41, 0x18000
	s_mov_b32 s42, 0x20000
	s_mov_b32 s43, 0x28000
	s_mov_b32 s44, 0x30000
	s_mov_b32 s45, 0x38000
	s_mov_b32 s46, 0x40000
	s_mov_b32 s47, 0x48000
	s_mov_b32 s48, 0x50000
	s_mov_b32 s49, 0x58000
	s_mov_b32 s50, 0x60000
	s_mov_b32 s51, 0x68000
	s_mov_b32 s52, 0x70000
	s_mov_b32 s53, 0x78000
	v_add_u32_e32 v92, 0x410, v81
	v_add_u32_e32 v93, 0x418, v81
	v_add_u32_e32 v94, 0x820, v81
	v_add_u32_e32 v95, 0x828, v81
	v_add_u32_e32 v96, 0xc30, v81
	v_add_u32_e32 v97, 0xc38, v81
	v_add_u32_e32 v98, 0x1040, v81
	v_add_u32_e32 v99, 0x1048, v81
	v_add_u32_e32 v100, 0x1450, v81
	v_add_u32_e32 v101, 0x1458, v81
	v_add_u32_e32 v102, 0x1860, v81
	v_add_u32_e32 v103, 0x1868, v81
	v_add_u32_e32 v104, 0x1c70, v81
	v_add_u32_e32 v105, 0x1c78, v81
	v_add_u32_e32 v106, 0x2080, v81
	v_add_u32_e32 v107, 0x2088, v81
	v_add_u32_e32 v108, 0x2490, v81
	v_add_u32_e32 v109, 0x2498, v81
	v_add_u32_e32 v110, 0x28a0, v81
	v_add_u32_e32 v111, 0x28a8, v81
	v_add_u32_e32 v112, 0x2cb0, v81
	v_add_u32_e32 v113, 0x2cb8, v81
	v_add_u32_e32 v114, 0x30c0, v81
	v_add_u32_e32 v115, 0x30c8, v81
	v_add_u32_e32 v116, 0x34d0, v81
	v_add_u32_e32 v117, 0x34d8, v81
	v_add_u32_e32 v118, 0x38e0, v81
	v_add_u32_e32 v119, 0x38e8, v81
	v_add_u32_e32 v120, 0x3cf0, v81
	v_lshlrev_b32_e32 v72, 2, v2
	s_mov_b32 s54, 0xf0000
	s_mov_b32 s55, 0x10e000
	s_mov_b32 s56, 0x12c000
	s_mov_b32 s57, 0x14a000
	s_mov_b32 s58, 0x168000
	s_mov_b32 s59, 0x186000
	s_mov_b32 s60, 0x1a4000
	s_mov_b32 s61, 0x1c2000
	v_lshlrev_b32_e32 v68, 2, v4
	v_add_u32_e32 v121, 0x3cf8, v81
	v_lshlrev_b32_e32 v74, 1, v0
	v_add_u32_e32 v122, v1, v3
	s_branch .LBB0_163
.LBB0_162:
	v_readlane_b32 s2, v253, 34
	s_add_i32 s15, s15, s2
	s_movk_i32 s100, 0x1c7f
	s_cmpk_eq_i32 s86, 0x100
	s_cselect_b32 s100, 0x1a7f, s100
	s_cmp_gt_i32 s15, s100
	s_cbranch_scc1 .LBB0_209

.LBB0_427:
	s_or_b64 exec, exec, s[0:1]
	v_mov_b32_e32 v0, v252
	v_readlane_b32 s3, v254, 33
	v_readfirstlane_b32 s0, v0
	s_ashr_i32 s2, s0, 6
	s_add_i32 s26, s3, s2
	s_cmpk_lg_i32 s86, 0x100
	s_cbranch_scc1 .Lseam1_init_done
	s_sub_i32 s3, s96, 0xc0
	s_lshl_b32 s26, s3, 3
	s_add_i32 s26, s26, s2
	s_addk_i32 s26, 0x1a80
	s_cmp_lt_i32 s3, 0
	s_cselect_b32 s26, 0x2180, s26
